# adds: stick-breaking epilogue transposes the output block through the wave's LDS so each store instruction writes 8 full 128-byte rows
# speedup vs baseline: 1.0150x; 1.0023x over previous
; __device__ __forceinline__ unsigned cvtpk(float lo, float hi) { f32x2_t v = {lo, hi}; bf16x2_t b = __builtin_convertvector(v, bf16x2_t); return __builtin_bit_cast(unsigned, b); }
; template <bool DRY> __device__ __forceinline__ void sb_unit(int b, int h, int qi, bf16_t* Pm, const bf16_t* VT) {
;     ...
; #pragma unroll
;     for (int g = 0; g < 4; ++g) {
;         u32x2 w0, w1;
;         w0.x = cvtpk(o0[4 * g], o0[4 * g + 1]); w0.y = cvtpk(o0[4 * g + 2], o0[4 * g + 3]);
;         w1.x = cvtpk(o1[4 * g], o1[4 * g + 1]); w1.y = cvtpk(o1[4 * g + 2], o1[4 * g + 3]);
;         if (!DRY || R == 1234.56789f) { *(u32x2*)(qrow + 8 * g + 4 * hi) = w0; *(u32x2*)(qrow + 32 + 8 * g + 4 * hi) = w1; }
;     }
.Lsbl_exit:
	s_waitcnt vmcnt(0)
	s_or_b64 exec, exec, s[34:35]
	v_readfirstlane_b32 s4, v234
	s_lshl_b32 s4, s4, 8
	v_and_b32_e32 v36, 31, v234
	v_mul_u32_u24_e32 v37, 0x90, v36
	v_lshl_add_u32 v37, v86, 2, v37
	v_add_u32_e32 v37, s4, v37
	v_and_b32_e32 v38, 63, v234
	v_lshrrev_b32_e32 v39, 3, v38
	v_and_b32_e32 v38, 7, v38
	v_mul_u32_u24_e32 v40, 0x90, v39
	v_lshl_add_u32 v40, v38, 4, v40
	v_add_u32_e32 v40, s4, v40
	v_sub_u32_e32 v42, v39, v36
	v_mul_lo_u32 v42, v42, s24
	v_lshl_add_u32 v42, v38, 4, v42
	v_ashrrev_i32_e32 v43, 31, v42
	v_lshl_add_u64 v[0:1], v[84:85], 0, v[42:43]
	s_lshl_b32 s4, s24, 3
	s_mov_b32 s5, 0
	v_lshl_add_u64 v[44:45], v[0:1], 0, s[4:5]
	v_lshl_add_u64 v[46:47], v[44:45], 0, s[4:5]
	v_lshl_add_u64 v[48:49], v[46:47], 0, s[4:5]
	s_nop 4
	v_cvt_pk_bf16_f32 v4, v4, v5
	v_cvt_pk_bf16_f32 v5, v6, v7
	v_cvt_pk_bf16_f32 v6, v8, v9
	v_cvt_pk_bf16_f32 v7, v10, v11
	v_cvt_pk_bf16_f32 v8, v12, v13
	v_cvt_pk_bf16_f32 v9, v14, v15
	v_cvt_pk_bf16_f32 v10, v16, v17
	v_cvt_pk_bf16_f32 v11, v18, v19
	v_cvt_pk_bf16_f32 v20, v20, v21
	v_cvt_pk_bf16_f32 v21, v22, v23
	v_cvt_pk_bf16_f32 v22, v24, v25
	v_cvt_pk_bf16_f32 v23, v26, v27
	v_cvt_pk_bf16_f32 v24, v28, v29
	v_cvt_pk_bf16_f32 v25, v30, v31
	v_cvt_pk_bf16_f32 v26, v32, v33
	v_cvt_pk_bf16_f32 v27, v34, v35
	v_permlane32_swap_b32_e32 v4, v6
	v_permlane32_swap_b32_e32 v5, v7
	v_permlane32_swap_b32_e32 v8, v10
	v_permlane32_swap_b32_e32 v9, v11
	v_permlane32_swap_b32_e32 v20, v22
	v_permlane32_swap_b32_e32 v21, v23
	v_permlane32_swap_b32_e32 v24, v26
	v_permlane32_swap_b32_e32 v25, v27
	ds_write_b128 v37, v[4:7]
	ds_write_b128 v37, v[8:11] offset:32
	ds_write_b128 v37, v[20:23] offset:64
	ds_write_b128 v37, v[24:27] offset:96
	s_waitcnt lgkmcnt(0)
	ds_read_b128 v[4:7], v40
	ds_read_b128 v[8:11], v40 offset:1152
	ds_read_b128 v[20:23], v40 offset:2304
	ds_read_b128 v[24:27], v40 offset:3456
	s_waitcnt lgkmcnt(3)
	global_store_dwordx4 v[0:1], v[4:7], off offset:1280
	s_waitcnt lgkmcnt(2)
	global_store_dwordx4 v[44:45], v[8:11], off offset:1280
	s_waitcnt lgkmcnt(1)
	global_store_dwordx4 v[46:47], v[20:23], off offset:1280
	s_waitcnt lgkmcnt(0)
	global_store_dwordx4 v[48:49], v[24:27], off offset:1280
	v_add_u32_e32 v3, s26, v3
	s_movk_i32 s4, 0x1fff
	v_cmp_lt_i32_e32 vcc, s4, v3
	s_or_b64 s[40:41], vcc, s[40:41]
	v_add_u16_e32 v87, s26, v87
	s_andn2_b64 exec, exec, s[40:41]
	s_cbranch_execnz .LBB0_741
